# adds early issue of the rms row-scale loads before the gemm_in K loop
# baseline (speedup 1.0000x reference)
; DI int tid_() { int t = threadIdx.x; asm volatile("" : "+v"(t)); return t; }
; #define LASP __attribute__((address_space(3)))
; DI void gemm_dma(f32x4 (&acc)[4][4], const bf16_t* Ap, int lda, const bf16_t* Bp, int ldb, int K, char* lds) {
;   const int tid = tid_(), wave = __builtin_amdgcn_readfirstlane(tid >> 6), lane = tid & 63;
;   const int wm = wave >> 1, wn = wave & 1, l15 = lane & 15, quad = lane >> 4;
;   const int nk = K / 64;
;   const int lrow = lane >> 3, lpc = lane & 7;
;   const bf16_t* ga[4]; const bf16_t* gb[4];
; #pragma unroll
;   for (int i = 0; i < 4; ++i) {
;     const int row = (wave * 4 + i) * 8 + lrow; const int q = lpc ^ (row & 7);
;     ga[i] = Ap + (size_t)row * lda + q * 8; gb[i] = Bp + (size_t)row * ldb + q * 8;
;   }
;   auto issue = [&](int kt) {
;     char* sb = lds + (kt & 1) * 32768 + wave * 4096;
; #pragma unroll
;     for (int i = 0; i < 4; ++i) {
;       __builtin_amdgcn_global_load_lds((const unsigned*)(ga[i] + kt * 64), (LASP unsigned*)(sb + i * 1024), 16, 0, 0);
;       __builtin_amdgcn_global_load_lds((const unsigned*)(gb[i] + kt * 64), (LASP unsigned*)(sb + 16384 + i * 1024), 16, 0, 0);
;     }
;   };
;   const int sw = l15 & 7;
;   const unsigned lbase = (unsigned)(size_t)(LASP char*)lds;
;   const unsigned a0 = (unsigned)((wm * 64 + l15) * 128 + ((quad ^ sw) * 16)), a1 = (unsigned)((wm * 64 + l15) * 128 + (((4 + quad) ^ sw) * 16));
;   const unsigned b0 = 16384u + (unsigned)((wn * 64 + l15) * 128 + ((quad ^ sw) * 16)), b1 = 16384u + (unsigned)((wn * 64 + l15) * 128 + (((4 + quad) ^ sw) * 16));
;   asm volatile("s_waitcnt vmcnt(0)" ::: "memory");
;   __builtin_amdgcn_s_barrier();
;   asm volatile("" ::: "memory");
;   issue(0);
; DI void phase_gemm_in(const Params& p, int l, char* lds) {
;     ...
;     const int g = xcd_tile(r, NTN * NTM); if (g < 0) break;
;     int mt, nt; tile_decode(g, NTM, NTN, mt, nt);
;     f32x4 acc[4][4]; zero_acc(acc);
;     gemm_dma(acc, p.hn + (size_t)mt * 128 * DM, DM, Wt + (size_t)nt * 128 * DM, DM, DM, lds);
;     const int colb = nt * 128 + wn * 64 + quad * 4;
;     {
; #pragma unroll
;       for (int mi = 0; mi < 4; ++mi) {
;         const float rs = rsqrtf(p.ss1[mt * 128 + wm * 64 + mi * 16 + l15] * (1.0f / 1024.0f) + 1e-6f);
.LBB0_68:
	s_mul_hi_u32 s0, s20, 0x5397829d
	s_lshr_b32 s21, s0, 7
	s_lshl_b32 s0, s21, 3
	s_sub_i32 s1, 0x84, s0
	s_min_i32 s1, s1, 8
	s_abs_i32 s2, s1
	v_cvt_f32_u32_e32 v0, s2
	s_sub_i32 s24, 0, s2
	s_mul_i32 s3, s21, 0xfffffe78
	s_add_i32 s3, s3, s20
	v_rcp_iflag_f32_e32 v0, v0
	s_abs_i32 s22, s3
	s_xor_b32 s23, s3, s1
	s_ashr_i32 s23, s23, 31
	v_mul_f32_e32 v0, 0x4f7ffffe, v0
	v_cvt_u32_f32_e32 v0, v0
	v_readlane_b32 s68, v251, 49
	v_readlane_b32 s72, v251, 53
	v_mov_b32_e32 v26, v212
	v_readfirstlane_b32 s25, v0
	s_mul_i32 s24, s24, s25
	s_mul_hi_u32 s24, s25, s24
	s_add_i32 s25, s25, s24
	s_mul_hi_u32 s24, s22, s25
	s_mul_i32 s25, s24, s2
	s_sub_i32 s22, s22, s25
	s_add_i32 s26, s24, 1
	s_sub_i32 s25, s22, s2
	s_cmp_ge_u32 s22, s2
	s_cselect_b32 s24, s26, s24
	s_cselect_b32 s22, s25, s22
	s_add_i32 s25, s24, 1
	s_cmp_ge_u32 s22, s2
	s_cselect_b32 s2, s25, s24
	s_add_i32 s3, s3, s0
	s_xor_b32 s0, s2, s23
	s_sub_i32 s0, s0, s23
	s_mul_i32 s30, s0, s1
	s_sub_i32 s2, s3, s30
	s_ashr_i32 s3, s2, 31
	s_lshl_b64 s[22:23], s[2:3], 18
	s_add_u32 s24, s8, s22
	s_addc_u32 s25, s9, s23
	s_ashr_i32 s1, s0, 31
	s_lshl_b64 s[22:23], s[0:1], 18
	v_readlane_b32 s73, v251, 54
	s_add_u32 s26, s72, s22
	s_addc_u32 s27, s73, s23
	v_readfirstlane_b32 s1, v26
	s_ashr_i32 s3, s1, 6
	v_bfe_u32 v0, v26, 3, 3
	s_waitcnt lgkmcnt(0)
	v_lshl_or_b32 v2, s3, 5, v0
	v_bitop3_b32 v0, v0, v26, 7 bitop3:0x78
	v_bfe_u32 v27, v26, 4, 2
	v_and_b32_e32 v28, 7, v26
	v_lshlrev_b32_e32 v0, 4, v0
	v_ashrrev_i32_e32 v3, 31, v2
	v_and_b32_e32 v29, 15, v26
	v_lshl_add_u64 v[4:5], s[24:25], 0, v[0:1]
	v_lshlrev_b64 v[8:9], 11, v[2:3]
	v_or_b32_e32 v14, 8, v2
	s_lshr_b32 s24, s1, 1
	v_bitop3_b32 v26, v27, v26, 7 bitop3:0x78
	v_bitop3_b32 v27, v27, v28, 4 bitop3:0x36
	v_and_or_b32 v28, s1, 64, v29
	s_lshl_b32 s1, s3, 12
	v_lshl_add_u64 v[6:7], s[26:27], 0, v[0:1]
	v_lshl_add_u64 v[10:11], v[4:5], 0, v[8:9]
	v_ashrrev_i32_e32 v15, 31, v14
	s_waitcnt vmcnt(0)
	s_barrier
	s_add_i32 s3, s1, 0x4000
	s_mov_b32 m0, s1
	v_lshl_add_u64 v[12:13], v[6:7], 0, v[8:9]
	v_lshlrev_b64 v[14:15], 11, v[14:15]
	v_or_b32_e32 v20, 16, v2
	global_load_lds_dwordx4 v[10:11], off
	s_mov_b32 m0, s3
	v_lshl_add_u64 v[16:17], v[4:5], 0, v[14:15]
	v_ashrrev_i32_e32 v21, 31, v20
	global_load_lds_dwordx4 v[12:13], off
	s_or_b32 m0, s1, 0x400
	v_lshl_add_u64 v[18:19], v[6:7], 0, v[14:15]
	v_lshlrev_b64 v[20:21], 11, v[20:21]
	v_or_b32_e32 v2, 24, v2
	global_load_lds_dwordx4 v[16:17], off
	s_add_i32 m0, s1, 0x4400
	v_lshl_add_u64 v[22:23], v[4:5], 0, v[20:21]
	v_ashrrev_i32_e32 v3, 31, v2
	global_load_lds_dwordx4 v[18:19], off
	s_or_b32 m0, s1, 0x800
	v_lshl_add_u64 v[24:25], v[6:7], 0, v[20:21]
	v_lshlrev_b64 v[2:3], 11, v[2:3]
	global_load_lds_dwordx4 v[22:23], off
	s_add_i32 m0, s1, 0x4800
	v_lshl_add_u64 v[4:5], v[4:5], 0, v[2:3]
	global_load_lds_dwordx4 v[24:25], off
	s_or_b32 m0, s1, 0xc00
	v_lshl_add_u64 v[6:7], v[6:7], 0, v[2:3]
	global_load_lds_dwordx4 v[4:5], off
	s_add_i32 m0, s1, 0x4c00
	s_sub_i32 s3, s20, s30
	global_load_lds_dwordx4 v[6:7], off
	s_mulk_i32 s21, 0x180
	s_sub_i32 s20, s3, s21
	s_ashr_i32 s21, s20, 31
	s_and_b32 s24, s24, 0x1ffffc0
	s_lshl_b64 s[20:21], s[20:21], 18
	v_or_b32_e32 v30, s24, v29
	v_lshl_add_u64 v[4:5], s[20:21], 0, v[8:9]
	v_readlane_b32 s24, v254, 19
	v_or_b32_e32 v4, v4, v0
	v_readlane_b32 s25, v254, 20
	v_readlane_b32 s26, v254, 21
	v_readlane_b32 s27, v254, 22
	v_lshl_add_u64 v[66:67], s[24:25], 0, v[4:5]
	v_lshl_add_u64 v[4:5], s[22:23], 0, v[8:9]
	v_or_b32_e32 v4, v4, v0
	v_lshl_add_u64 v[68:69], s[26:27], 0, v[4:5]
	v_lshl_add_u64 v[4:5], s[20:21], 0, v[14:15]
	v_or_b32_e32 v4, v4, v0
	v_lshl_add_u64 v[74:75], s[24:25], 0, v[4:5]
	v_lshl_add_u64 v[4:5], s[22:23], 0, v[14:15]
	v_or_b32_e32 v4, v4, v0
	v_lshl_add_u64 v[76:77], s[26:27], 0, v[4:5]
	v_lshl_add_u64 v[4:5], s[20:21], 0, v[20:21]
	v_or_b32_e32 v4, v4, v0
	v_lshl_add_u64 v[78:79], s[24:25], 0, v[4:5]
	v_lshl_add_u64 v[4:5], s[22:23], 0, v[20:21]
	v_or_b32_e32 v4, v4, v0
	v_lshl_add_u64 v[80:81], s[26:27], 0, v[4:5]
	v_lshl_add_u64 v[4:5], s[20:21], 0, v[2:3]
	v_lshl_add_u64 v[2:3], s[22:23], 0, v[2:3]
	v_lshlrev_b32_e32 v30, 7, v30
	v_lshlrev_b32_e32 v26, 4, v26
	v_lshlrev_b32_e32 v27, 4, v27
	v_lshlrev_b32_e32 v28, 7, v28
	v_or_b32_e32 v4, v4, v0
	v_or_b32_e32 v2, v2, v0
	v_mov_b32_e32 v50, 0
	v_or_b32_e32 v86, v30, v26
	v_or_b32_e32 v87, v30, v27
	v_or3_b32 v89, v28, v26, s91
	v_or3_b32 v88, v28, v27, s91
	v_lshl_add_u64 v[82:83], s[24:25], 0, v[4:5]
	v_lshl_add_u64 v[84:85], s[26:27], 0, v[2:3]
	s_mov_b64 s[22:23], 0
	s_mov_b32 s3, 0
	v_mov_b32_e32 v51, v50
	v_mov_b32_e32 v52, v50
	v_mov_b32_e32 v53, v50
	v_mov_b32_e32 v2, v50
	v_mov_b32_e32 v3, v50
	v_mov_b32_e32 v4, v50
	v_mov_b32_e32 v5, v50
	v_mov_b32_e32 v6, v50
	v_mov_b32_e32 v7, v50
	v_mov_b32_e32 v8, v50
	v_mov_b32_e32 v9, v50
	v_mov_b32_e32 v10, v50
	v_mov_b32_e32 v11, v50
	v_mov_b32_e32 v12, v50
	v_mov_b32_e32 v13, v50
	v_mov_b32_e32 v14, v50
	v_mov_b32_e32 v15, v50
	v_mov_b32_e32 v16, v50
	v_mov_b32_e32 v17, v50
	v_mov_b32_e32 v18, v50
	v_mov_b32_e32 v19, v50
	v_mov_b32_e32 v20, v50
	v_mov_b32_e32 v21, v50
	v_mov_b32_e32 v22, v50
	v_mov_b32_e32 v23, v50
	v_mov_b32_e32 v24, v50
	v_mov_b32_e32 v25, v50
	v_mov_b32_e32 v26, v50
	v_mov_b32_e32 v27, v50
	v_mov_b32_e32 v28, v50
	v_mov_b32_e32 v29, v50
	v_mov_b32_e32 v30, v50
	v_mov_b32_e32 v31, v50
	v_mov_b32_e32 v32, v50
	v_mov_b32_e32 v33, v50
	v_mov_b32_e32 v34, v50
	v_mov_b32_e32 v35, v50
	v_mov_b32_e32 v36, v50
	v_mov_b32_e32 v37, v50
	v_mov_b32_e32 v38, v50
	v_mov_b32_e32 v39, v50
	v_mov_b32_e32 v40, v50
	v_mov_b32_e32 v41, v50
	v_mov_b32_e32 v42, v50
	v_mov_b32_e32 v43, v50
	v_mov_b32_e32 v44, v50
	v_mov_b32_e32 v45, v50
	v_mov_b32_e32 v46, v50
	v_mov_b32_e32 v47, v50
	v_mov_b32_e32 v48, v50
	v_mov_b32_e32 v49, v50
	v_mov_b32_e32 v54, v50
	v_mov_b32_e32 v55, v50
	v_mov_b32_e32 v56, v50
	v_mov_b32_e32 v57, v50
	v_mov_b32_e32 v58, v50
	v_mov_b32_e32 v59, v50
	v_mov_b32_e32 v60, v50
	v_mov_b32_e32 v61, v50
	v_mov_b32_e32 v62, v50
	v_mov_b32_e32 v63, v50
	v_mov_b32_e32 v64, v50
	v_mov_b32_e32 v65, v50
	v_readlane_b32 s69, v251, 50
	v_readlane_b32 s70, v251, 51
	v_readlane_b32 s71, v251, 52
	v_readlane_b32 s74, v251, 55
	v_readlane_b32 s75, v251, 56
	v_readlane_b32 s76, v251, 57
	v_readlane_b32 s77, v251, 58
	v_readlane_b32 s78, v251, 59
	v_readlane_b32 s79, v251, 60
	v_readlane_b32 s80, v251, 61
	v_readlane_b32 s81, v251, 62
	v_readlane_b32 s82, v251, 63
	v_readlane_b32 s83, v252, 0
	s_lshl_b32 s20, s2, 7
	v_add_u32_e32 v222, s20, v71
	v_readlane_b32 s20, v254, 52
	v_readlane_b32 s21, v254, 53
	v_ashrrev_i32_e32 v223, 31, v222
	s_nop 1
	v_lshl_add_u64 v[222:223], v[222:223], 2, s[20:21]
	global_load_dword v224, v[222:223], off
	global_load_dword v225, v[222:223], off offset:64
	global_load_dword v226, v[222:223], off offset:128
	global_load_dword v227, v[222:223], off offset:192
; DI void gemm_dma(f32x4 (&acc)[4][4], const bf16_t* Ap, int lda, const bf16_t* Bp, int ldb, int K, char* lds) {
;     ...
;   for (int kt = 0; kt < nk; ++kt) {
;     asm volatile("s_waitcnt vmcnt(0)" ::: "memory");
;     __builtin_amdgcn_s_barrier();
;     asm volatile("" ::: "memory");
;     if (kt + 1 < nk) issue(kt + 1);
;     const unsigned sa = lbase + (unsigned)((kt & 1) * 32768);
;     bf16x8 af[4], bfr[4], ag[4], bg[4];
;     asm volatile("ds_read_b128 %0, %8\n\tds_read_b128 %1, %8 offset:2048\n\tds_read_b128 %2, %8 offset:4096\n\tds_read_b128 %3, %8 offset:6144\n\t"
;                  "ds_read_b128 %4, %9\n\tds_read_b128 %5, %9 offset:2048\n\tds_read_b128 %6, %9 offset:4096\n\tds_read_b128 %7, %9 offset:6144"
;                  : "=&v"(af[0]), "=&v"(af[1]), "=&v"(af[2]), "=&v"(af[3]), "=&v"(bfr[0]), "=&v"(bfr[1]), "=&v"(bfr[2]), "=&v"(bfr[3])
;                  : "v"(sa + a0), "v"(sa + b0) : "memory");
;     asm volatile("ds_read_b128 %0, %16\n\tds_read_b128 %1, %16 offset:2048\n\tds_read_b128 %2, %16 offset:4096\n\tds_read_b128 %3, %16 offset:6144\n\t"
;                  "ds_read_b128 %4, %17\n\tds_read_b128 %5, %17 offset:2048\n\tds_read_b128 %6, %17 offset:4096\n\tds_read_b128 %7, %17 offset:6144\n\t"
;                  "s_waitcnt lgkmcnt(8)"
;                  : "=&v"(ag[0]), "=&v"(ag[1]), "=&v"(ag[2]), "=&v"(ag[3]), "=&v"(bg[0]), "=&v"(bg[1]), "=&v"(bg[2]), "=&v"(bg[3]),
;                    "+v"(af[0]), "+v"(af[1]), "+v"(af[2]), "+v"(af[3]), "+v"(bfr[0]), "+v"(bfr[1]), "+v"(bfr[2]), "+v"(bfr[3])
;                  : "v"(sa + a1), "v"(sa + b1) : "memory");
; #pragma unroll
;     for (int mi = 0; mi < 4; ++mi)
; #pragma unroll
;       for (int ni = 0; ni < 4; ++ni) acc[mi][ni] = __builtin_amdgcn_mfma_f32_16x16x32_bf16(bfr[ni], af[mi], acc[mi][ni], 0, 0, 0);
;     asm volatile("s_waitcnt lgkmcnt(0)" : "+v"(ag[0]), "+v"(ag[1]), "+v"(ag[2]), "+v"(ag[3]), "+v"(bg[0]), "+v"(bg[1]), "+v"(bg[2]), "+v"(bg[3]) :: "memory");
; #pragma unroll
;     for (int mi = 0; mi < 4; ++mi)
; #pragma unroll
;       for (int ni = 0; ni < 4; ++ni) acc[mi][ni] = __builtin_amdgcn_mfma_f32_16x16x32_bf16(bg[ni], ag[mi], acc[mi][ni], 0, 0, 0);
;   }
.LBB0_69:
	s_add_i32 s20, s3, 0x8000
	s_and_b32 s3, s3, 0x8000
	s_and_b32 s21, s20, 0x8000
	v_add_u32_e32 v0, s3, v86
	v_or_b32_e32 v122, s3, v89
	s_waitcnt vmcnt(0)
	v_add_u32_e32 v154, s3, v87
	v_add_u32_e32 v155, s3, v88
	s_add_i32 s3, s1, s21
	s_waitcnt vmcnt(0)
	s_barrier
	v_lshl_add_u64 v[90:91], v[66:67], 0, s[22:23]
	s_add_i32 s21, s3, 0x4000
	s_mov_b32 m0, s3
	v_lshl_add_u64 v[92:93], v[68:69], 0, s[22:23]
	global_load_lds_dwordx4 v[90:91], off
	s_mov_b32 m0, s21
	v_lshl_add_u64 v[94:95], v[74:75], 0, s[22:23]
	global_load_lds_dwordx4 v[92:93], off
	s_add_i32 m0, s3, 0x400
	v_lshl_add_u64 v[96:97], v[76:77], 0, s[22:23]
	global_load_lds_dwordx4 v[94:95], off
	s_add_i32 m0, s3, 0x4400
	v_lshl_add_u64 v[98:99], v[78:79], 0, s[22:23]
	global_load_lds_dwordx4 v[96:97], off
	s_add_i32 m0, s3, 0x800
	v_lshl_add_u64 v[100:101], v[80:81], 0, s[22:23]
	global_load_lds_dwordx4 v[98:99], off
	s_add_i32 m0, s3, 0x4800
	v_lshl_add_u64 v[102:103], v[82:83], 0, s[22:23]
	global_load_lds_dwordx4 v[100:101], off
	s_add_i32 m0, s3, 0xc00
	v_lshl_add_u64 v[104:105], v[84:85], 0, s[22:23]
	global_load_lds_dwordx4 v[102:103], off
	s_add_i32 m0, s3, 0x4c00
	s_add_u32 s22, s22, 0x80
	global_load_lds_dwordx4 v[104:105], off
	ds_read_b128 v[90:93], v0
	ds_read_b128 v[94:97], v0 offset:2048
	ds_read_b128 v[98:101], v0 offset:4096
	ds_read_b128 v[102:105], v0 offset:6144
	ds_read_b128 v[106:109], v122
	ds_read_b128 v[110:113], v122 offset:2048
	ds_read_b128 v[114:117], v122 offset:4096
	ds_read_b128 v[118:121], v122 offset:6144
	s_addc_u32 s23, s23, 0
	ds_read_b128 v[122:125], v154
	ds_read_b128 v[126:129], v154 offset:2048
	ds_read_b128 v[130:133], v154 offset:4096
	ds_read_b128 v[134:137], v154 offset:6144
	ds_read_b128 v[138:141], v155
	ds_read_b128 v[142:145], v155 offset:2048
	ds_read_b128 v[146:149], v155 offset:4096
	ds_read_b128 v[150:153], v155 offset:6144
	s_waitcnt lgkmcnt(8)
	s_cmpk_lg_i32 s22, 0x780
	v_mfma_f32_16x16x32_bf16 v[62:65], v[106:109], v[90:93], v[62:65]
	s_waitcnt lgkmcnt(0)
	s_mov_b32 s3, s20
	v_mfma_f32_16x16x32_bf16 v[58:61], v[110:113], v[90:93], v[58:61]
	v_mfma_f32_16x16x32_bf16 v[54:57], v[114:117], v[90:93], v[54:57]
	v_mfma_f32_16x16x32_bf16 v[46:49], v[118:121], v[90:93], v[46:49]
	v_mfma_f32_16x16x32_bf16 v[42:45], v[106:109], v[94:97], v[42:45]
	v_mfma_f32_16x16x32_bf16 v[38:41], v[110:113], v[94:97], v[38:41]
	v_mfma_f32_16x16x32_bf16 v[34:37], v[114:117], v[94:97], v[34:37]
	v_mfma_f32_16x16x32_bf16 v[30:33], v[118:121], v[94:97], v[30:33]
	v_mfma_f32_16x16x32_bf16 v[26:29], v[106:109], v[98:101], v[26:29]
	v_mfma_f32_16x16x32_bf16 v[22:25], v[110:113], v[98:101], v[22:25]
	v_mfma_f32_16x16x32_bf16 v[18:21], v[114:117], v[98:101], v[18:21]
	v_mfma_f32_16x16x32_bf16 v[14:17], v[118:121], v[98:101], v[14:17]
	v_mfma_f32_16x16x32_bf16 v[10:13], v[106:109], v[102:105], v[10:13]
	v_mfma_f32_16x16x32_bf16 v[6:9], v[110:113], v[102:105], v[6:9]
	v_mfma_f32_16x16x32_bf16 v[2:5], v[114:117], v[102:105], v[2:5]
	v_mfma_f32_16x16x32_bf16 v[50:53], v[118:121], v[102:105], v[50:53]
	v_mfma_f32_16x16x32_bf16 v[62:65], v[138:141], v[122:125], v[62:65]
	v_mfma_f32_16x16x32_bf16 v[58:61], v[142:145], v[122:125], v[58:61]
	v_mfma_f32_16x16x32_bf16 v[54:57], v[146:149], v[122:125], v[54:57]
	v_mfma_f32_16x16x32_bf16 v[46:49], v[150:153], v[122:125], v[46:49]
	v_mfma_f32_16x16x32_bf16 v[42:45], v[138:141], v[126:129], v[42:45]
	v_mfma_f32_16x16x32_bf16 v[38:41], v[142:145], v[126:129], v[38:41]
	v_mfma_f32_16x16x32_bf16 v[34:37], v[146:149], v[126:129], v[34:37]
	v_mfma_f32_16x16x32_bf16 v[30:33], v[150:153], v[126:129], v[30:33]
	v_mfma_f32_16x16x32_bf16 v[26:29], v[138:141], v[130:133], v[26:29]
	v_mfma_f32_16x16x32_bf16 v[22:25], v[142:145], v[130:133], v[22:25]
	v_mfma_f32_16x16x32_bf16 v[18:21], v[146:149], v[130:133], v[18:21]
	v_mfma_f32_16x16x32_bf16 v[14:17], v[150:153], v[130:133], v[14:17]
	v_mfma_f32_16x16x32_bf16 v[10:13], v[138:141], v[134:137], v[10:13]
	v_mfma_f32_16x16x32_bf16 v[6:9], v[142:145], v[134:137], v[6:9]
	v_mfma_f32_16x16x32_bf16 v[2:5], v[146:149], v[134:137], v[2:5]
	v_mfma_f32_16x16x32_bf16 v[50:53], v[150:153], v[134:137], v[50:53]
	s_cbranch_scc1 .LBB0_69
; DI void gemm_dma(f32x4 (&acc)[4][4], const bf16_t* Ap, int lda, const bf16_t* Bp, int ldb, int K, char* lds) {
;     ...
; #pragma unroll
;     for (int mi = 0; mi < 4; ++mi)
; #pragma unroll
;       for (int ni = 0; ni < 4; ++ni) acc[mi][ni] = __builtin_amdgcn_mfma_f32_16x16x32_bf16(bfr[ni], af[mi], acc[mi][ni], 0, 0, 0);
;     asm volatile("s_waitcnt lgkmcnt(0)" : "+v"(ag[0]), "+v"(ag[1]), "+v"(ag[2]), "+v"(ag[3]), "+v"(bg[0]), "+v"(bg[1]), "+v"(bg[2]), "+v"(bg[3]) :: "memory");
; #pragma unroll
;     for (int mi = 0; mi < 4; ++mi)
; #pragma unroll
;       for (int ni = 0; ni < 4; ++ni) acc[mi][ni] = __builtin_amdgcn_mfma_f32_16x16x32_bf16(bg[ni], ag[mi], acc[mi][ni], 0, 0, 0);
;   }
; DI void phase_gemm_in(const Params& p, int l, char* lds) {
;     ...
;         const float rs = rsqrtf(p.ss1[mt * 128 + wm * 64 + mi * 16 + l15] * (1.0f / 1024.0f) + 1e-6f);
; #pragma unroll
;         for (int ni = 0; ni < 4; ++ni) acc[mi][ni] = acc[mi][ni] * rs;
;       }
;     }
;     int kind;
;     if (nt < 13) kind = 0; else if (nt < 17) kind = 1; else if (nt < 21) kind = 2; else if (nt < 25) kind = 3; else if (nt < 29) kind = 4; else if (nt < 33) kind = 1; else kind = 5;
	s_waitcnt vmcnt(0)
	s_barrier
	v_add_u32_e32 v0, 0x8000, v86
	v_or_b32_e32 v86, 0x8000, v89
	ds_read_b128 v[66:69], v0
	ds_read_b128 v[74:77], v0 offset:2048
	ds_read_b128 v[78:81], v0 offset:4096
	ds_read_b128 v[82:85], v0 offset:6144
	ds_read_b128 v[90:93], v86
	ds_read_b128 v[94:97], v86 offset:2048
	ds_read_b128 v[98:101], v86 offset:4096
	ds_read_b128 v[102:105], v86 offset:6144
	v_add_u32_e32 v0, 0x8000, v87
	v_add_u32_e32 v134, 0x8000, v88
	ds_read_b128 v[86:89], v0
	ds_read_b128 v[106:109], v0 offset:2048
	ds_read_b128 v[110:113], v0 offset:4096
	ds_read_b128 v[114:117], v0 offset:6144
	ds_read_b128 v[118:121], v134
	ds_read_b128 v[122:125], v134 offset:2048
	ds_read_b128 v[126:129], v134 offset:4096
	ds_read_b128 v[130:133], v134 offset:6144
	s_waitcnt lgkmcnt(8)
	s_lshl_b32 s46, s2, 7
	v_mfma_f32_16x16x32_bf16 v[62:65], v[90:93], v[66:69], v[62:65]
	s_waitcnt lgkmcnt(0)
	v_readlane_b32 s20, v254, 52
	v_readlane_b32 s21, v254, 53
	v_mfma_f32_16x16x32_bf16 v[46:49], v[102:105], v[66:69], v[46:49]
	s_barrier
	v_mfma_f32_16x16x32_bf16 v[42:45], v[90:93], v[74:77], v[42:45]
	v_readlane_b32 s22, v254, 54
	v_readlane_b32 s23, v254, 55
	v_readlane_b32 s24, v254, 56
	v_mfma_f32_16x16x32_bf16 v[38:41], v[94:97], v[74:77], v[38:41]
	v_readlane_b32 s25, v254, 57
	v_readlane_b32 s26, v254, 58
	v_readlane_b32 s27, v254, 59
	v_mfma_f32_16x16x32_bf16 v[34:37], v[98:101], v[74:77], v[34:37]
	s_cmp_gt_i32 s0, 12
	s_mov_b64 s[2:3], 0
	s_cselect_b64 s[30:31], -1, 0
	v_mfma_f32_16x16x32_bf16 v[30:33], v[102:105], v[74:77], v[30:33]
	s_cmp_lt_i32 s0, 13
	s_mov_b64 s[26:27], 0
	s_mov_b64 s[24:25], 0
	v_mfma_f32_16x16x32_bf16 v[26:29], v[90:93], v[78:81], v[26:29]
	s_mov_b64 s[22:23], 0
	v_mfma_f32_16x16x32_bf16 v[18:21], v[98:101], v[78:81], v[18:21]
	v_mfma_f32_16x16x32_bf16 v[14:17], v[102:105], v[78:81], v[14:17]
	v_mfma_f32_16x16x32_bf16 v[134:137], v[98:101], v[66:69], v[54:57]
	v_mfma_f32_16x16x32_bf16 v[54:57], v[118:121], v[86:89], v[62:65]
	v_mfma_f32_16x16x32_bf16 v[62:65], v[130:133], v[86:89], v[46:49]
	v_mfma_f32_16x16x32_bf16 v[46:49], v[118:121], v[106:109], v[42:45]
	v_mfma_f32_16x16x32_bf16 v[42:45], v[122:125], v[106:109], v[38:41]
	v_mfma_f32_16x16x32_bf16 v[38:41], v[126:129], v[106:109], v[34:37]
	v_mfma_f32_16x16x32_bf16 v[34:37], v[130:133], v[106:109], v[30:33]
	v_mfma_f32_16x16x32_bf16 v[30:33], v[118:121], v[110:113], v[26:29]
	v_mfma_f32_16x16x32_bf16 v[26:29], v[126:129], v[110:113], v[18:21]
	v_mfma_f32_16x16x32_bf16 v[18:21], v[130:133], v[110:113], v[14:17]
	s_nop 2
	v_add_u32_e32 v14, s46, v71
	v_ashrrev_i32_e32 v15, 31, v14
	v_lshl_add_u64 v[74:75], v[14:15], 2, s[20:21]
	v_mfma_f32_16x16x32_bf16 v[58:61], v[94:97], v[66:69], v[58:61]
	v_mfma_f32_16x16x32_bf16 v[66:69], v[102:105], v[82:85], v[50:53]
	v_mov_b32_e32 v0, v224
	v_mov_b32_e32 v105, v225
	v_mov_b32_e32 v104, v226
	v_mov_b32_e32 v102, v227
	v_mfma_f32_16x16x32_bf16 v[22:25], v[94:97], v[78:81], v[22:25]
	v_mfma_f32_16x16x32_bf16 v[10:13], v[90:93], v[82:85], v[10:13]
	v_mfma_f32_16x16x32_bf16 v[6:9], v[94:97], v[82:85], v[6:9]
	v_mfma_f32_16x16x32_bf16 v[2:5], v[98:101], v[82:85], v[2:5]
	v_mfma_f32_16x16x32_bf16 v[50:53], v[122:125], v[86:89], v[58:61]
	v_mfma_f32_16x16x32_bf16 v[58:61], v[126:129], v[86:89], v[134:137]
	v_mfma_f32_16x16x32_bf16 v[22:25], v[122:125], v[110:113], v[22:25]
	v_mfma_f32_16x16x32_bf16 v[14:17], v[118:121], v[114:117], v[10:13]
	v_mfma_f32_16x16x32_bf16 v[10:13], v[122:125], v[114:117], v[6:9]
	v_mfma_f32_16x16x32_bf16 v[6:9], v[126:129], v[114:117], v[2:5]
	v_mfma_f32_16x16x32_bf16 v[2:5], v[130:133], v[114:117], v[66:69]
	s_cbranch_scc1 .LBB0_77
	s_cmp_lt_u32 s0, 17
	s_cbranch_scc1 .LBB0_75
	s_cmp_lt_u32 s0, 21
	s_cbranch_scc1 .LBB0_76
	s_mov_b64 s[22:23], -1
	s_cmp_lt_u32 s0, 25
	s_cbranch_scc1 .LBB0_77
	s_sub_i32 s1, s0, 29
	s_cmp_lt_u32 s1, 4
	s_cselect_b64 s[2:3], -1, 0
	s_cmp_gt_u32 s0, 32
	s_mov_b64 s[22:23], 0
	s_cselect_b64 s[26:27], -1, 0
	s_branch .LBB0_77
